# strategy 7.11 loop-edge rotation: nsa_attn_sw tile loops issue the next-tile K/V loads and the loop-carried v_mov copies before the loop-back barrier instead of after it
# baseline (speedup 1.0000x reference)
; template <int MODE, class MaskF> ...
;     if (tiles == 0ull) return;
;     int kb = __builtin_ctzll(tiles); tiles &= tiles - 1ull; int cur = 0;
;     f32x4 OL[2]; OL[0] = (f32x4){0.f, 0.f, 0.f, 0.f}; OL[1] = (f32x4){0.f, 0.f, 0.f, 0.f};
;     { Stage st; load_tile<MODE != 1>(src, kb * 64, tid, st); store_tile<MODE != 1>(lds, tid, st); }
;     __syncthreads();
;     for (;;) {
;         const bool more = tiles != 0ull; int nkb = 0;
;         if (more) { nkb = __builtin_ctzll(tiles); tiles &= tiles - 1ull; }
; __device__ __forceinline__ void nsa_attn_sw(const Ctx& c, const bf16* Q, const bf16* T, const bf16* VT, const float* Gt, const float* NACC, float* NACC2, const unsigned long long* SMg, bf16* OUT) {
;     ...
;         NSA_UNIT_PROLOGUE
;         unsigned long long um = SMg[(size_t)bg * SEQ + t0 + lane];
; #pragma unroll
;         for (int o = 1; o < 64; o <<= 1) { const unsigned lo_ = __shfl_xor((unsigned)um, o), hi_ = __shfl_xor((unsigned)(um >> 32), o); um |= ((unsigned long long)hi_ << 32) | lo_; }
;         const unsigned long long umu = ((unsigned long long)__builtin_amdgcn_readfirstlane((unsigned)(um >> 32)) << 32) | (unsigned)__builtin_amdgcn_readfirstlane((unsigned)um);
;         f32x4 O[8][2]; float m[2], l[2]; const float invl[2] = {0.f, 0.f};
;         { fa::SelMask mk; mk.qb = qb; mk.tq[0] = tq[0]; mk.tq[1] = tq[1]; mk.sm[0] = SMg[(size_t)bg * SEQ + tq[0]]; mk.sm[1] = SMg[(size_t)bg * SEQ + tq[1]];
;           const unsigned long long tiles = umu & ((2ull << qb) - 1ull);
;           fa::Src src{T + 2 * NT_STRIDE + (size_t)bg * 4096 * 128, 128, VT + (size_t)bg * 128 * 4096, 4096};
;           m[0] = m[1] = -1e30f; l[0] = l[1] = 0.f;
; #pragma unroll
;           for (int dt = 0; dt < 8; ++dt) { O[dt][0] = (f32x4){0.f, 0.f, 0.f, 0.f}; O[dt][1] = (f32x4){0.f, 0.f, 0.f, 0.f}; }
;           fa::run<0>(c.lds, src, tiles, Qf, O, m, l, invl, mk, c.tid, c.wave, l15, lg);
.LBB0_2315:
	s_lshr_b32 s0, s36, 4
	s_and_b32 s0, s0, 14
	s_and_b32 s1, s36, 1
	s_or_b32 s38, s0, s1
	s_lshl_b32 s0, s36, 6
	s_lshl_b32 s18, s37, 6
	s_and_b32 s6, s0, 0x3000
	s_lshl_b32 s7, s38, 2
	s_lshl_b32 s0, s38, 15
	s_add_u32 s9, s54, s0
	s_addc_u32 s10, s55, 0
	s_lshl_b64 s[0:1], s[18:19], 3
	s_add_u32 s0, s9, s0
	s_addc_u32 s1, s10, s1
	global_load_dwordx2 v[6:7], v251, s[0:1]
	v_add_u32_e32 v225, s18, v172
	v_add_u32_e32 v226, s18, v210
	v_and_or_b32 v227, s7, 12, v233
	v_mov_b32_e32 v187, v5
	v_mov_b32_e32 v189, v5
	v_add_u32_e32 v186, s6, v225
	v_add_u32_e32 v188, s6, v226
	v_lshlrev_b32_e32 v4, 8, v227
	v_lshlrev_b64 v[184:185], 12, v[186:187]
	v_lshlrev_b64 v[182:183], 12, v[188:189]
	v_lshl_add_u64 v[8:9], v[228:229], 0, v[4:5]
	v_lshl_add_u64 v[20:21], v[8:9], 0, v[184:185]
	v_lshl_add_u64 v[36:37], v[8:9], 0, v[182:183]
	global_load_dwordx4 v[8:11], v[20:21], off
	global_load_dwordx4 v[12:15], v[20:21], off offset:64
	global_load_dwordx4 v[16:19], v[20:21], off offset:128
	s_nop 0
	global_load_dwordx4 v[20:23], v[20:21], off offset:192
	s_nop 0
	global_load_dwordx4 v[24:27], v[36:37], off
	global_load_dwordx4 v[28:31], v[36:37], off offset:64
	global_load_dwordx4 v[32:35], v[36:37], off offset:128
	s_nop 0
	global_load_dwordx4 v[36:39], v[36:37], off offset:192
	s_lshl_b64 s[6:7], 2, s37
	s_add_u32 s22, s6, -1
	s_addc_u32 s23, s7, -1
	s_lshl_b32 s39, s38, 19
	v_lshlrev_b32_e32 v192, 1, v174
	v_lshlrev_b32_e32 v190, 1, v176
	s_waitcnt vmcnt(0)
	ds_bpermute_b32 v4, v175, v7
	ds_bpermute_b32 v40, v175, v6
	s_waitcnt lgkmcnt(0)
	v_or_b32_e32 v4, v4, v7
	v_or_b32_e32 v6, v40, v6
	ds_bpermute_b32 v7, v177, v4
	ds_bpermute_b32 v40, v177, v6
	s_waitcnt lgkmcnt(1)
	v_or_b32_e32 v4, v7, v4
	s_waitcnt lgkmcnt(0)
	v_or_b32_e32 v6, v40, v6
	ds_bpermute_b32 v7, v206, v4
	ds_bpermute_b32 v40, v206, v6
	s_waitcnt lgkmcnt(1)
	v_or_b32_e32 v4, v7, v4
	s_waitcnt lgkmcnt(0)
	v_or_b32_e32 v6, v40, v6
	ds_bpermute_b32 v7, v207, v4
	ds_bpermute_b32 v40, v207, v6
	s_waitcnt lgkmcnt(1)
	v_or_b32_e32 v4, v7, v4
	s_waitcnt lgkmcnt(0)
	v_or_b32_e32 v6, v40, v6
	ds_bpermute_b32 v7, v208, v4
	ds_bpermute_b32 v40, v208, v6
	s_waitcnt lgkmcnt(1)
	v_or_b32_e32 v4, v7, v4
	s_waitcnt lgkmcnt(0)
	v_or_b32_e32 v6, v40, v6
	ds_bpermute_b32 v7, v209, v4
	ds_bpermute_b32 v40, v209, v6
	s_waitcnt lgkmcnt(1)
	v_or_b32_e32 v4, v7, v4
	s_waitcnt lgkmcnt(0)
	v_or_b32_e32 v6, v40, v6
	v_readfirstlane_b32 s7, v4
	v_readfirstlane_b32 s6, v6
	s_and_b64 s[6:7], s[6:7], s[22:23]
	s_cmp_eq_u64 s[6:7], 0
	s_cbranch_scc1 .LBB0_2334
	global_load_dwordx2 v[194:195], v252, s[0:1]
	global_load_dwordx2 v[196:197], v252, s[0:1] offset:32
	s_lshl_b32 s0, s38, 20
	s_add_u32 s0, s56, s0
	s_addc_u32 s1, s57, 0
	s_lshl_b32 s9, s39, 1
	s_add_u32 s10, s21, s9
	s_addc_u32 s11, s26, 0
	s_add_u32 s24, s6, -1
	s_ff1_i32_b64 s41, s[6:7]
	s_addc_u32 s25, s7, -1
	s_and_b64 s[24:25], s[24:25], s[6:7]
	s_lshl_b32 s6, s41, 6
	v_or_b32_e32 v4, s6, v231
	v_lshlrev_b32_e32 v4, 8, v4
	v_lshl_add_u64 v[6:7], s[10:11], 0, v[4:5]
	v_or_b32_e32 v4, s6, v211
	v_lshlrev_b32_e32 v4, 8, v4
	v_mov_b32_e32 v193, v5
	v_lshl_add_u64 v[48:49], s[10:11], 0, v[4:5]
	v_lshl_add_u64 v[6:7], v[6:7], 0, v[192:193]
	v_lshl_add_u64 v[48:49], v[48:49], 0, v[192:193]
	global_load_dwordx4 v[40:43], v[6:7], off
	s_lshl_b32 s18, s41, 7
	global_load_dwordx4 v[48:51], v[48:49], off
	v_lshl_add_u64 v[6:7], s[0:1], 0, v[178:179]
	v_lshl_add_u64 v[44:45], v[6:7], 0, s[18:19]
	v_mov_b32_e32 v191, v5
	v_lshl_add_u64 v[44:45], v[44:45], 0, v[190:191]
	v_lshl_add_u64 v[56:57], s[0:1], 0, v[180:181]
	global_load_dwordx4 v[44:47], v[44:45], off
	v_lshl_add_u64 v[52:53], v[56:57], 0, s[18:19]
	v_lshl_add_u64 v[52:53], v[52:53], 0, v[190:191]
	global_load_dwordx4 v[52:55], v[52:53], off
	v_lshl_add_u64 v[200:201], v[6:7], 0, v[190:191]
	v_mov_b32_e32 v6, v5
	v_mov_b32_e32 v7, v5
	v_lshl_add_u64 v[202:203], v[56:57], 0, v[190:191]
	v_mov_b32_e32 v4, v5
	v_mov_b32_e32 v128, 0
	v_mov_b64_e32 v[74:75], v[6:7]
	v_mov_b64_e32 v[78:79], v[6:7]
	v_mov_b64_e32 v[82:83], v[6:7]
	v_mov_b64_e32 v[86:87], v[6:7]
	v_mov_b64_e32 v[58:59], v[6:7]
	v_mov_b64_e32 v[90:91], v[6:7]
	v_mov_b64_e32 v[62:63], v[6:7]
	v_mov_b64_e32 v[94:95], v[6:7]
	v_mov_b64_e32 v[66:67], v[6:7]
	v_mov_b64_e32 v[98:99], v[6:7]
	v_mov_b64_e32 v[70:71], v[6:7]
	v_mov_b64_e32 v[102:103], v[6:7]
	v_lshl_add_u64 v[198:199], s[10:11], 0, v[192:193]
	s_mov_b32 s40, 0
	v_mov_b32_e32 v191, 0xf149f2ca
	v_mov_b64_e32 v[72:73], v[4:5]
	v_mov_b64_e32 v[76:77], v[4:5]
	v_mov_b64_e32 v[80:81], v[4:5]
	v_mov_b64_e32 v[84:85], v[4:5]
	v_mov_b64_e32 v[56:57], v[4:5]
	v_mov_b64_e32 v[88:89], v[4:5]
	v_mov_b64_e32 v[60:61], v[4:5]
	v_mov_b64_e32 v[92:93], v[4:5]
	v_mov_b64_e32 v[64:65], v[4:5]
	v_mov_b64_e32 v[96:97], v[4:5]
	v_mov_b64_e32 v[68:69], v[4:5]
	v_mov_b64_e32 v[100:101], v[4:5]
	v_mov_b32_e32 v193, 0xf149f2ca
	v_mov_b32_e32 v129, v128
	v_mov_b32_e32 v130, v128
	v_mov_b32_e32 v131, v128
	v_mov_b32_e32 v124, v128
	v_mov_b32_e32 v125, v128
	v_mov_b32_e32 v126, v128
	v_mov_b32_e32 v127, v128
	v_mov_b32_e32 v104, v128
	v_mov_b32_e32 v105, v128
	v_mov_b32_e32 v106, v128
	v_mov_b32_e32 v107, v128
	s_waitcnt vmcnt(3)
	ds_write_b128 v232, v[40:43]
	s_waitcnt vmcnt(1)
	ds_write_b128 v165, v[44:47] offset:17408
	ds_write_b128 v222, v[48:51]
	s_waitcnt vmcnt(0)
	ds_write_b128 v223, v[52:55] offset:17408
	v_mov_b64_e32 v[42:43], v[6:7]
	v_mov_b64_e32 v[46:47], v[6:7]
	v_mov_b64_e32 v[50:51], v[6:7]
	v_mov_b64_e32 v[54:55], v[6:7]
	v_mov_b64_e32 v[40:41], v[4:5]
	v_mov_b64_e32 v[44:45], v[4:5]
	v_mov_b64_e32 v[48:49], v[4:5]
	v_mov_b64_e32 v[52:53], v[4:5]
	s_cmp_eq_u64 s[24:25], 0
	s_cbranch_scc1 .Lmy_rotA_sel
	s_ff1_i32_b64 s100, s[24:25]
	s_lshl_b32 s99, s100, 6
	s_lshl_b32 s100, s100, 7
	s_mov_b32 s101, 0
	v_or_b32_e32 v114, s99, v231
	v_or_b32_e32 v122, s99, v211
	v_lshlrev_b32_e32 v114, 8, v114
	v_lshlrev_b32_e32 v122, 8, v122
	v_mov_b32_e32 v115, 0
	v_mov_b32_e32 v123, 0
	v_lshl_add_u64 v[112:113], v[198:199], 0, v[114:115]
	v_lshl_add_u64 v[108:109], v[200:201], 0, s[100:101]
	v_lshl_add_u64 v[120:121], v[198:199], 0, v[122:123]
	v_lshl_add_u64 v[116:117], v[202:203], 0, s[100:101]
	s_waitcnt vmcnt(0)
	global_load_dwordx4 v[112:115], v[112:113], off
	global_load_dwordx4 v[108:111], v[108:109], off
	global_load_dwordx4 v[120:123], v[120:121], off
	global_load_dwordx4 v[116:119], v[116:117], off

; #define LAS __attribute__((address_space(3)))
; template <int MODE, class MaskF> ...
;     ...
;     const LAS unsigned char* kbase = buf + l15 * KS_STRIDE + lg * 16;
;     bf16x8 kf[2][2];
; #pragma unroll
;     for (int q = 0; q < 2; ++q) kf[0][q] = *(const LAS bf16x8*)(kbase + q * 16 * KS_STRIDE);
; #pragma unroll
;     for (int h = 0; h < 8; ++h) { const int ks = h >> 1, n0 = (h & 1) * 2;
;         if (h < 7) { const int ks1 = (h + 1) >> 1, n1 = ((h + 1) & 1) * 2;
; #pragma unroll
;             for (int q = 0; q < 2; ++q) kf[(h + 1) & 1][q] = *(const LAS bf16x8*)(kbase + (n1 + q) * 16 * KS_STRIDE + ks1 * 64); }
;         __builtin_amdgcn_sched_barrier(0);
;         __builtin_amdgcn_s_setprio(1);
; #pragma unroll
;         for (int q = 0; q < 2; ++q)
; #pragma unroll
;             for (int mi = 0; mi < 2; ++mi) S[n0 + q][mi] = __builtin_amdgcn_mfma_f32_16x16x32_bf16(kf[h & 1][q], Qf[mi][ks], S[n0 + q][mi], 0, 0, 0);
;         __builtin_amdgcn_s_setprio(0);
;         __builtin_amdgcn_sched_barrier(0);
;     }
;     const float NEG = -__builtin_inff();
;     float mx[2] = {NEG, NEG};
;     if (mf.need(kb)) {
; #pragma unroll
;         for (int nt = 0; nt < 4; ++nt)
; #pragma unroll
;             for (int mi = 0; mi < 2; ++mi)
; #pragma unroll
;                 for (int r = 0; r < 4; ++r) { const float sv = mf.valid(kb, 16 * nt + 4 * lg + r, mi) ? S[nt][mi][r] : NEG; S[nt][mi][r] = sv; mx[mi] = fmaxf(mx[mi], sv); }
;     } else {
; #pragma unroll
;         for (int nt = 0; nt < 4; ++nt)
; #pragma unroll
;             for (int mi = 0; mi < 2; ++mi)
; #pragma unroll
;                 for (int r = 0; r < 4; ++r) mx[mi] = fmaxf(mx[mi], S[nt][mi][r]);
.LBB0_2317:
.Lnopf_sel:
	s_mul_i32 s0, s40, 0x8c00
	s_add_i32 s42, s0, 0
	v_add3_u32 v4, s42, v3, v230
	ds_read_b128 v[132:135], v4
	ds_read_b128 v[136:139], v4 offset:4352
	ds_read_b128 v[140:143], v4 offset:8704
	ds_read_b128 v[144:147], v4 offset:13056
	s_setprio 1
	s_waitcnt lgkmcnt(3)
	v_mfma_f32_16x16x32_bf16 v[148:151], v[132:135], v[8:11], 0
	v_mfma_f32_16x16x32_bf16 v[132:135], v[132:135], v[24:27], 0
	s_waitcnt lgkmcnt(2)
	v_mfma_f32_16x16x32_bf16 v[152:155], v[136:139], v[8:11], 0
	v_mfma_f32_16x16x32_bf16 v[136:139], v[136:139], v[24:27], 0
	s_setprio 0
	ds_read_b128 v[156:159], v4 offset:64
	ds_read_b128 v[160:163], v4 offset:4416
	s_setprio 1
	s_waitcnt lgkmcnt(3)
	v_mfma_f32_16x16x32_bf16 v[234:237], v[140:143], v[8:11], 0
	v_mfma_f32_16x16x32_bf16 v[140:143], v[140:143], v[24:27], 0
	s_waitcnt lgkmcnt(2)
	v_mfma_f32_16x16x32_bf16 v[238:241], v[144:147], v[8:11], 0
	v_mfma_f32_16x16x32_bf16 v[144:147], v[144:147], v[24:27], 0
	s_setprio 0
	ds_read_b128 v[242:245], v4 offset:8768
	ds_read_b128 v[246:249], v4 offset:13120
	s_setprio 1
	s_waitcnt lgkmcnt(3)
	v_mfma_f32_16x16x32_bf16 v[148:151], v[156:159], v[12:15], v[148:151]
	v_mfma_f32_16x16x32_bf16 v[132:135], v[156:159], v[28:31], v[132:135]
	s_waitcnt lgkmcnt(2)
	v_mfma_f32_16x16x32_bf16 v[152:155], v[160:163], v[12:15], v[152:155]
	v_mfma_f32_16x16x32_bf16 v[136:139], v[160:163], v[28:31], v[136:139]
	s_setprio 0
	ds_read_b128 v[156:159], v4 offset:128
	ds_read_b128 v[160:163], v4 offset:4480
	s_setprio 1
	s_waitcnt lgkmcnt(3)
	v_mfma_f32_16x16x32_bf16 v[140:143], v[242:245], v[28:31], v[140:143]
	s_waitcnt lgkmcnt(2)
	v_mfma_f32_16x16x32_bf16 v[144:147], v[246:249], v[28:31], v[144:147]
	v_mfma_f32_16x16x32_bf16 v[234:237], v[242:245], v[12:15], v[234:237]
	v_mfma_f32_16x16x32_bf16 v[238:241], v[246:249], v[12:15], v[238:241]
	s_setprio 0
	ds_read_b128 v[242:245], v4 offset:8832
	ds_read_b128 v[246:249], v4 offset:13184
	s_setprio 1
	s_waitcnt lgkmcnt(3)
	v_mfma_f32_16x16x32_bf16 v[148:151], v[156:159], v[16:19], v[148:151]
	v_mfma_f32_16x16x32_bf16 v[132:135], v[156:159], v[32:35], v[132:135]
	s_waitcnt lgkmcnt(2)
	v_mfma_f32_16x16x32_bf16 v[152:155], v[160:163], v[16:19], v[152:155]
	v_mfma_f32_16x16x32_bf16 v[136:139], v[160:163], v[32:35], v[136:139]
	s_setprio 0
	ds_read_b128 v[156:159], v4 offset:192
	ds_read_b128 v[160:163], v4 offset:4544
	s_setprio 1
	s_waitcnt lgkmcnt(3)
	v_mfma_f32_16x16x32_bf16 v[234:237], v[242:245], v[16:19], v[234:237]
	v_mfma_f32_16x16x32_bf16 v[242:245], v[242:245], v[32:35], v[140:143]
	s_waitcnt lgkmcnt(2)
	v_mfma_f32_16x16x32_bf16 v[238:241], v[246:249], v[16:19], v[238:241]
	v_mfma_f32_16x16x32_bf16 v[246:249], v[246:249], v[32:35], v[144:147]
	s_setprio 0
	ds_read_b128 v[166:169], v4 offset:8896
	ds_read_b128 v[218:221], v4 offset:13248
	s_setprio 1
	s_waitcnt lgkmcnt(3)
	v_mfma_f32_16x16x32_bf16 v[148:151], v[156:159], v[20:23], v[148:151]
	v_mfma_f32_16x16x32_bf16 v[144:147], v[156:159], v[36:39], v[132:135]
	s_waitcnt lgkmcnt(2)
	v_mfma_f32_16x16x32_bf16 v[152:155], v[160:163], v[20:23], v[152:155]
	v_mfma_f32_16x16x32_bf16 v[140:143], v[160:163], v[36:39], v[136:139]
	s_setprio 0
	s_setprio 1
	s_waitcnt lgkmcnt(1)
	v_mfma_f32_16x16x32_bf16 v[156:159], v[166:169], v[20:23], v[234:237]
	v_mfma_f32_16x16x32_bf16 v[136:139], v[166:169], v[36:39], v[242:245]
	s_waitcnt lgkmcnt(0)
	v_mfma_f32_16x16x32_bf16 v[160:163], v[218:221], v[20:23], v[238:241]
	v_mfma_f32_16x16x32_bf16 v[132:135], v[218:221], v[36:39], v[246:249]
	s_setprio 0
	s_cmp_eq_u32 s41, s37
	s_cselect_b64 s[0:1], -1, 0
	s_lshl_b64 s[6:7], 1, s41
	s_cmp_lg_u32 s41, s37
	v_and_b32_e32 v205, s7, v195
	v_and_b32_e32 v204, s6, v194
	s_cbranch_scc0 .LBB0_2320
	v_and_b32_e32 v7, v205, v197
	v_and_b32_e32 v6, v204, v196
	v_cmp_ne_u64_e32 vcc, 0, v[6:7]
	s_cmp_eq_u64 vcc, exec
	s_mov_b64 s[0:1], -1
	s_cbranch_scc0 .LBB0_2321
	v_max3_f32 v4, v148, s29, v149
	v_max3_f32 v4, v4, v150, v151
	v_max3_f32 v6, v144, s29, v145
	v_max3_f32 v6, v6, v146, v147
	v_max3_f32 v4, v4, v152, v153
	v_max3_f32 v4, v4, v154, v155
	v_max3_f32 v6, v6, v140, v141
	v_max3_f32 v6, v6, v142, v143
	v_max3_f32 v4, v4, v156, v157
	v_max3_f32 v4, v4, v158, v159
	v_max3_f32 v6, v6, v136, v137
	v_max3_f32 v7, v6, v138, v139
	v_max3_f32 v4, v4, v160, v161
	v_max3_f32 v6, v4, v162, v163
	v_max3_f32 v4, v7, v132, v133
	v_max3_f32 v7, v4, v134, v135
	s_mov_b64 s[0:1], 0
	s_branch .LBB0_2321

; #define LAS __attribute__((address_space(3)))
; template <int MODE, class MaskF> ...
;     ...
;         const bool more = tiles != 0ull; int nkb = 0;
;         if (more) { nkb = __builtin_ctzll(tiles); tiles &= tiles - 1ull; }
;         bf16x8 Pf[2][2];
;         tile_qk<MODE>(lds + cur * BUF_BYTES, Qf, O, m, l, invl, kb, mf, (LAS float*)(lds + PS_OFF), wave, l15, lg, Pf, OL);
;         __builtin_amdgcn_sched_barrier(0);
;         Stage st;
;         if (more) load_tile<MODE != 1>(src, nkb * 64, tid, st);
;         if constexpr (MODE != 1) tile_pv(lds + cur * BUF_BYTES, Pf, O, l15, lg, OL, MODE == 0);
;         if (more) store_tile<MODE != 1>(lds + (cur ^ 1) * BUF_BYTES, tid, st);
;         __syncthreads();
;         if (!more) break;
;         kb = nkb; cur ^= 1;
;     }
.LBB0_2331:
	s_add_u32 s6, s24, -1
	s_addc_u32 s7, s25, -1
	s_and_b64 s[24:25], s[6:7], s[24:25]
	s_andn2_b64 vcc, exec, s[0:1]
	s_cmp_eq_u64 s[24:25], 0
	s_cbranch_scc1 .Lmy_rotB_sel
	s_ff1_i32_b64 s100, s[24:25]
	s_lshl_b32 s99, s100, 6
	s_lshl_b32 s100, s100, 7
	s_mov_b32 s101, 0
	v_or_b32_e32 v114, s99, v231
	v_or_b32_e32 v122, s99, v211
	v_lshlrev_b32_e32 v114, 8, v114
	v_lshlrev_b32_e32 v122, 8, v122
	v_mov_b32_e32 v115, 0
	v_mov_b32_e32 v123, 0
	v_lshl_add_u64 v[112:113], v[198:199], 0, v[114:115]
	v_lshl_add_u64 v[108:109], v[200:201], 0, s[100:101]
	v_lshl_add_u64 v[120:121], v[198:199], 0, v[122:123]
	v_lshl_add_u64 v[116:117], v[202:203], 0, s[100:101]
	s_waitcnt vmcnt(0)
	global_load_dwordx4 v[112:115], v[112:113], off
	global_load_dwordx4 v[108:111], v[108:109], off
	global_load_dwordx4 v[120:123], v[120:121], off
	global_load_dwordx4 v[116:119], v[116:117], off
.Lmy_rotB_sel:
	v_mov_b32_e32 v124, v128
	v_mov_b32_e32 v125, v129
	v_mov_b32_e32 v126, v130
	v_mov_b32_e32 v127, v131
	s_waitcnt lgkmcnt(0)
	s_barrier
	s_cbranch_vccnz .LBB0_2317

; __device__ __forceinline__ float sigmoidf_(float x) { return 1.f / (1.f + __expf(-x)); }
; __device__ __forceinline__ void nsa_attn_sw(const Ctx& c, const bf16* Q, const bf16* T, const bf16* VT, const float* Gt, const float* NACC, float* NACC2, const unsigned long long* SMg, bf16* OUT) {
;     ...
; #pragma unroll
;           for (int mi = 0; mi < 2; ++mi) { float lt = l[mi]; lt += __shfl_xor(lt, 16); lt += __shfl_xor(lt, 32); const float sc = sigmoidf_(Gt[(size_t)grow[mi] * 48 + (hcol[mi] >> 7) * 3 + 1]) / lt;
; #pragma unroll
;               for (int dt = 0; dt < 8; ++dt) { const size_t off = (size_t)grow[mi] * 2048 + hcol[mi] + 16 * dt + 4 * lg; *(f32x4*)(NACC2 + off) = *(const f32x4*)(NACC + off) + O[dt][mi] * sc; } }
;         }
;         { fa::WinMask mk; mk.qb = qb; mk.tq[0] = tq[0]; mk.tq[1] = tq[1];
;           const int kb0 = qb - 8 < 0 ? 0 : qb - 8; const unsigned long long tiles = ((2ull << qb) - 1ull) & ~((1ull << kb0) - 1ull);
.LBB0_2335:
	ds_bpermute_b32 v4, v208, v7
	v_mov_b64_e32 v[104:105], s[16:17]
	v_mad_u64_u32 v[106:107], s[0:1], v186, s31, v[104:105]
	v_lshlrev_b32_e32 v200, 7, v227
	s_waitcnt lgkmcnt(0)
	v_add_f32_e32 v4, v7, v4
	ds_bpermute_b32 v7, v209, v4
	v_lshlrev_b64 v[196:197], 13, v[186:187]
	v_readlane_b32 s6, v254, 10
	v_readlane_b32 s7, v254, 11
	s_waitcnt lgkmcnt(0)
	v_add_f32_e32 v7, v4, v7
	v_mul_u32_u24_e32 v4, 3, v227
	v_lshlrev_b32_e32 v4, 2, v4
	v_lshl_add_u64 v[194:195], v[106:107], 0, v[4:5]
	global_load_dword v106, v[194:195], off offset:4
	s_waitcnt vmcnt(0)
	v_mul_f32_e32 v106, 0xbfb8aa3b, v106
	v_exp_f32_e32 v106, v106
	s_nop 0
	v_add_f32_e32 v106, 1.0, v106
	v_div_scale_f32 v107, s[0:1], v106, v106, 1.0
	v_rcp_f32_e32 v108, v107
	s_nop 0
	v_fma_f32 v109, -v107, v108, 1.0
	v_fmac_f32_e32 v108, v109, v108
	v_div_scale_f32 v109, vcc, 1.0, v106, 1.0
	v_mul_f32_e32 v110, v109, v108
	v_fma_f32 v111, -v107, v110, v109
	v_fmac_f32_e32 v110, v111, v108
	v_fma_f32 v107, -v107, v110, v109
	v_div_fmas_f32 v107, v107, v108, v110
	v_div_fixup_f32 v106, v107, v106, 1.0
	v_div_scale_f32 v107, s[0:1], v7, v7, v106
	v_rcp_f32_e32 v108, v107
	s_nop 0
	v_fma_f32 v109, -v107, v108, 1.0
	v_fmac_f32_e32 v108, v109, v108
	v_div_scale_f32 v109, vcc, v106, v7, v106
	v_mul_f32_e32 v110, v109, v108
	v_fma_f32 v111, -v107, v110, v109
	v_fmac_f32_e32 v110, v111, v108
	v_fma_f32 v107, -v107, v110, v109
	v_div_fmas_f32 v107, v107, v108, v110
	v_div_fixup_f32 v106, v107, v7, v106
	v_or_b32_e32 v7, v200, v170
	v_lshlrev_b32_e32 v7, 2, v7
	v_or_b32_e32 v108, v196, v7
	v_mov_b32_e32 v109, v197
	global_load_dwordx4 v[124:127], v108, s[6:7]
	global_load_dwordx4 v[128:131], v108, s[6:7] offset:64
	global_load_dwordx4 v[132:135], v108, s[6:7] offset:128
	global_load_dwordx4 v[136:139], v108, s[6:7] offset:192
	global_load_dwordx4 v[140:143], v108, s[6:7] offset:256
	global_load_dwordx4 v[144:147], v108, s[6:7] offset:320
	global_load_dwordx4 v[148:151], v108, s[6:7] offset:384
	global_load_dwordx4 v[152:155], v108, s[6:7] offset:448
	s_waitcnt vmcnt(7)
	v_pk_fma_f32 v[102:103], v[102:103], v[106:107], v[126:127] op_sel_hi:[1,0,1]
	v_pk_fma_f32 v[100:101], v[100:101], v[106:107], v[124:125] op_sel_hi:[1,0,1]
	global_store_dwordx4 v108, v[100:103], s[14:15]
	s_waitcnt vmcnt(7)
	v_pk_fma_f32 v[98:99], v[98:99], v[106:107], v[130:131] op_sel_hi:[1,0,1]
	v_pk_fma_f32 v[96:97], v[96:97], v[106:107], v[128:129] op_sel_hi:[1,0,1]
	global_store_dwordx4 v108, v[96:99], s[14:15] offset:64
	s_waitcnt vmcnt(7)
	v_pk_fma_f32 v[94:95], v[94:95], v[106:107], v[134:135] op_sel_hi:[1,0,1]
	v_pk_fma_f32 v[92:93], v[92:93], v[106:107], v[132:133] op_sel_hi:[1,0,1]
	global_store_dwordx4 v108, v[92:95], s[14:15] offset:128
	s_waitcnt vmcnt(7)
	v_pk_fma_f32 v[90:91], v[90:91], v[106:107], v[138:139] op_sel_hi:[1,0,1]
	v_pk_fma_f32 v[88:89], v[88:89], v[106:107], v[136:137] op_sel_hi:[1,0,1]
	global_store_dwordx4 v108, v[88:91], s[14:15] offset:192
	s_waitcnt vmcnt(7)
	v_pk_fma_f32 v[86:87], v[86:87], v[106:107], v[142:143] op_sel_hi:[1,0,1]
	v_pk_fma_f32 v[84:85], v[84:85], v[106:107], v[140:141] op_sel_hi:[1,0,1]
	global_store_dwordx4 v108, v[84:87], s[14:15] offset:256
	s_waitcnt vmcnt(7)
	v_pk_fma_f32 v[82:83], v[82:83], v[106:107], v[146:147] op_sel_hi:[1,0,1]
	v_pk_fma_f32 v[80:81], v[80:81], v[106:107], v[144:145] op_sel_hi:[1,0,1]
	global_store_dwordx4 v108, v[80:83], s[14:15] offset:320
	s_waitcnt vmcnt(7)
	v_pk_fma_f32 v[78:79], v[78:79], v[106:107], v[150:151] op_sel_hi:[1,0,1]
	v_pk_fma_f32 v[76:77], v[76:77], v[106:107], v[148:149] op_sel_hi:[1,0,1]
	global_store_dwordx4 v108, v[76:79], s[14:15] offset:384
	s_waitcnt vmcnt(7)
	v_pk_fma_f32 v[74:75], v[74:75], v[106:107], v[154:155] op_sel_hi:[1,0,1]
	v_pk_fma_f32 v[72:73], v[72:73], v[106:107], v[152:153] op_sel_hi:[1,0,1]
	global_store_dwordx4 v108, v[72:75], s[14:15] offset:448
	ds_bpermute_b32 v72, v208, v6
	s_waitcnt lgkmcnt(0)
	v_add_f32_e32 v6, v6, v72
	ds_bpermute_b32 v72, v209, v6
	s_waitcnt lgkmcnt(0)
	v_add_f32_e32 v6, v6, v72
	v_mad_u64_u32 v[72:73], s[0:1], v188, s31, v[104:105]
	v_lshl_add_u64 v[186:187], v[72:73], 0, v[4:5]
	global_load_dword v4, v[186:187], off offset:4
	v_lshlrev_b64 v[188:189], 13, v[188:189]
	s_waitcnt vmcnt(0)
	v_mul_f32_e32 v4, 0xbfb8aa3b, v4
	v_exp_f32_e32 v4, v4
	s_nop 0
	v_add_f32_e32 v4, 1.0, v4
	v_div_scale_f32 v72, s[0:1], v4, v4, 1.0
	v_rcp_f32_e32 v73, v72
	s_nop 0
	v_fma_f32 v74, -v72, v73, 1.0
	v_fmac_f32_e32 v73, v74, v73
	v_div_scale_f32 v74, vcc, 1.0, v4, 1.0
	v_mul_f32_e32 v75, v74, v73
	v_fma_f32 v76, -v72, v75, v74
	v_fmac_f32_e32 v75, v76, v73
	v_fma_f32 v72, -v72, v75, v74
	v_div_fmas_f32 v72, v72, v73, v75
	v_div_fixup_f32 v4, v72, v4, 1.0
	v_div_scale_f32 v72, s[0:1], v6, v6, v4
	v_rcp_f32_e32 v73, v72
	s_max_i32 s0, s37, 8
	s_add_i32 s0, s0, -8
	s_lshl_b64 s[0:1], -1, s0
	v_fma_f32 v74, -v72, v73, 1.0
	v_fmac_f32_e32 v73, v74, v73
	v_div_scale_f32 v74, vcc, v4, v6, v4
	v_mul_f32_e32 v75, v74, v73
	v_fma_f32 v76, -v72, v75, v74
	v_fmac_f32_e32 v75, v76, v73
	v_fma_f32 v72, -v72, v75, v74
	v_div_fmas_f32 v72, v72, v73, v75
	v_div_fixup_f32 v4, v72, v6, v4
	v_or_b32_e32 v6, v188, v7
	v_mov_b32_e32 v7, v189
	global_load_dwordx4 v[124:127], v6, s[6:7]
	global_load_dwordx4 v[128:131], v6, s[6:7] offset:64
	global_load_dwordx4 v[132:135], v6, s[6:7] offset:128
	global_load_dwordx4 v[136:139], v6, s[6:7] offset:192
	global_load_dwordx4 v[140:143], v6, s[6:7] offset:256
	global_load_dwordx4 v[144:147], v6, s[6:7] offset:320
	global_load_dwordx4 v[148:151], v6, s[6:7] offset:384
	global_load_dwordx4 v[152:155], v6, s[6:7] offset:448
	s_and_b64 s[0:1], s[0:1], s[22:23]
	s_cmp_eq_u64 s[0:1], 0
	s_waitcnt vmcnt(7)
; template <int MODE, class MaskF> ...
;     if (tiles == 0ull) return;
;     int kb = __builtin_ctzll(tiles); tiles &= tiles - 1ull; int cur = 0;
;     f32x4 OL[2]; OL[0] = (f32x4){0.f, 0.f, 0.f, 0.f}; OL[1] = (f32x4){0.f, 0.f, 0.f, 0.f};
;     { Stage st; load_tile<MODE != 1>(src, kb * 64, tid, st); store_tile<MODE != 1>(lds, tid, st); }
;     __syncthreads();
;     for (;;) {
;         const bool more = tiles != 0ull; int nkb = 0;
;         if (more) { nkb = __builtin_ctzll(tiles); tiles &= tiles - 1ull; }
; __device__ __forceinline__ void nsa_attn_sw(const Ctx& c, const bf16* Q, const bf16* T, const bf16* VT, const float* Gt, const float* NACC, float* NACC2, const unsigned long long* SMg, bf16* OUT) {
;     ...
;               for (int dt = 0; dt < 8; ++dt) { const size_t off = (size_t)grow[mi] * 2048 + hcol[mi] + 16 * dt + 4 * lg; *(f32x4*)(NACC2 + off) = *(const f32x4*)(NACC + off) + O[dt][mi] * sc; } }
;         }
;         { fa::WinMask mk; mk.qb = qb; mk.tq[0] = tq[0]; mk.tq[1] = tq[1];
;           const int kb0 = qb - 8 < 0 ? 0 : qb - 8; const unsigned long long tiles = ((2ull << qb) - 1ull) & ~((1ull << kb0) - 1ull);
;           fa::Src src{T + 4 * NT_STRIDE + (size_t)bg * 4096 * 128, 128, VT + (size_t)(16 + bg) * 128 * 4096, 4096};
;           m[0] = m[1] = -1e30f; l[0] = l[1] = 0.f;
; #pragma unroll
;           for (int dt = 0; dt < 8; ++dt) { O[dt][0] = (f32x4){0.f, 0.f, 0.f, 0.f}; O[dt][1] = (f32x4){0.f, 0.f, 0.f, 0.f}; }
;           fa::run<0>(c.lds, src, tiles, Qf, O, m, l, invl, mk, c.tid, c.wave, l15, lg);
	v_pk_fma_f32 v[70:71], v[70:71], v[4:5], v[126:127] op_sel_hi:[1,0,1]
	v_pk_fma_f32 v[68:69], v[68:69], v[4:5], v[124:125] op_sel_hi:[1,0,1]
	global_store_dwordx4 v6, v[68:71], s[14:15]
	s_waitcnt vmcnt(7)
	v_pk_fma_f32 v[66:67], v[66:67], v[4:5], v[130:131] op_sel_hi:[1,0,1]
	v_pk_fma_f32 v[64:65], v[64:65], v[4:5], v[128:129] op_sel_hi:[1,0,1]
	global_store_dwordx4 v6, v[64:67], s[14:15] offset:64
	s_waitcnt vmcnt(7)
	v_pk_fma_f32 v[62:63], v[62:63], v[4:5], v[134:135] op_sel_hi:[1,0,1]
	v_pk_fma_f32 v[60:61], v[60:61], v[4:5], v[132:133] op_sel_hi:[1,0,1]
	global_store_dwordx4 v6, v[60:63], s[14:15] offset:128
	s_waitcnt vmcnt(7)
	v_pk_fma_f32 v[58:59], v[58:59], v[4:5], v[138:139] op_sel_hi:[1,0,1]
	v_pk_fma_f32 v[56:57], v[56:57], v[4:5], v[136:137] op_sel_hi:[1,0,1]
	global_store_dwordx4 v6, v[56:59], s[14:15] offset:192
	s_waitcnt vmcnt(7)
	v_pk_fma_f32 v[54:55], v[54:55], v[4:5], v[142:143] op_sel_hi:[1,0,1]
	v_pk_fma_f32 v[52:53], v[52:53], v[4:5], v[140:141] op_sel_hi:[1,0,1]
	global_store_dwordx4 v6, v[52:55], s[14:15] offset:256
	s_waitcnt vmcnt(7)
	v_pk_fma_f32 v[50:51], v[50:51], v[4:5], v[146:147] op_sel_hi:[1,0,1]
	v_pk_fma_f32 v[48:49], v[48:49], v[4:5], v[144:145] op_sel_hi:[1,0,1]
	global_store_dwordx4 v6, v[48:51], s[14:15] offset:320
	s_waitcnt vmcnt(7)
	v_pk_fma_f32 v[46:47], v[46:47], v[4:5], v[150:151] op_sel_hi:[1,0,1]
	v_pk_fma_f32 v[44:45], v[44:45], v[4:5], v[148:149] op_sel_hi:[1,0,1]
	global_store_dwordx4 v6, v[44:47], s[14:15] offset:384
	s_waitcnt vmcnt(7)
	v_pk_fma_f32 v[42:43], v[42:43], v[4:5], v[154:155] op_sel_hi:[1,0,1]
	v_pk_fma_f32 v[40:41], v[40:41], v[4:5], v[152:153] op_sel_hi:[1,0,1]
	global_store_dwordx4 v6, v[40:43], s[14:15] offset:448
	s_cbranch_scc1 .LBB0_2351
	s_lshl_b32 s6, s38, 20
	s_add_u32 s6, s56, s6
	s_addc_u32 s7, s57, 0
	s_add_u32 s10, s6, 0x1000000
	s_addc_u32 s11, s7, 0
	s_lshl_b32 s6, s39, 1
	s_add_u32 s22, s27, s6
	s_addc_u32 s23, s28, 0
	s_add_u32 s6, s0, -1
	s_ff1_i32_b64 s38, s[0:1]
	s_addc_u32 s7, s1, -1
	s_and_b64 s[6:7], s[6:7], s[0:1]
	s_lshl_b32 s0, s38, 6
	v_or_b32_e32 v4, s0, v231
	v_lshlrev_b32_e32 v4, 8, v4
	v_lshl_add_u64 v[6:7], s[22:23], 0, v[4:5]
	v_or_b32_e32 v4, s0, v211
	v_lshlrev_b32_e32 v4, 8, v4
	v_mov_b32_e32 v193, v5
	v_lshl_add_u64 v[48:49], s[22:23], 0, v[4:5]
	v_lshl_add_u64 v[6:7], v[6:7], 0, v[192:193]
	v_lshl_add_u64 v[48:49], v[48:49], 0, v[192:193]
	global_load_dwordx4 v[40:43], v[6:7], off
	s_lshl_b32 s18, s38, 7
	global_load_dwordx4 v[48:51], v[48:49], off
	v_lshl_add_u64 v[6:7], s[10:11], 0, v[178:179]
	v_lshl_add_u64 v[44:45], v[6:7], 0, s[18:19]
	v_mov_b32_e32 v191, v5
	v_lshl_add_u64 v[44:45], v[44:45], 0, v[190:191]
	v_lshl_add_u64 v[56:57], s[10:11], 0, v[180:181]
	global_load_dwordx4 v[44:47], v[44:45], off
	v_lshl_add_u64 v[52:53], v[56:57], 0, s[18:19]
	v_lshl_add_u64 v[52:53], v[52:53], 0, v[190:191]
	global_load_dwordx4 v[52:55], v[52:53], off
	v_lshl_add_u64 v[198:199], v[6:7], 0, v[190:191]
	v_mov_b32_e32 v6, v5
	v_mov_b32_e32 v7, v5
	v_lshl_add_u64 v[190:191], v[56:57], 0, v[190:191]
	v_mov_b32_e32 v4, v5
	v_mov_b32_e32 v128, 0
	v_mov_b64_e32 v[74:75], v[6:7]
	v_mov_b64_e32 v[78:79], v[6:7]
	v_mov_b64_e32 v[82:83], v[6:7]
	v_mov_b64_e32 v[86:87], v[6:7]
	v_mov_b64_e32 v[58:59], v[6:7]
	v_mov_b64_e32 v[90:91], v[6:7]
	v_mov_b64_e32 v[62:63], v[6:7]
	v_mov_b64_e32 v[94:95], v[6:7]
	v_mov_b64_e32 v[66:67], v[6:7]
	v_mov_b64_e32 v[98:99], v[6:7]
	v_mov_b64_e32 v[70:71], v[6:7]
	v_mov_b64_e32 v[102:103], v[6:7]
	s_add_i32 s24, s37, -8
	v_lshl_add_u64 v[192:193], s[22:23], 0, v[192:193]
	s_mov_b32 s25, 0
	v_mov_b32_e32 v201, 0xf149f2ca
	v_mov_b64_e32 v[72:73], v[4:5]
	v_mov_b64_e32 v[76:77], v[4:5]
	v_mov_b64_e32 v[80:81], v[4:5]
	v_mov_b64_e32 v[84:85], v[4:5]
	v_mov_b64_e32 v[56:57], v[4:5]
	v_mov_b64_e32 v[88:89], v[4:5]
	v_mov_b64_e32 v[60:61], v[4:5]
	v_mov_b64_e32 v[92:93], v[4:5]
	v_mov_b64_e32 v[64:65], v[4:5]
	v_mov_b64_e32 v[96:97], v[4:5]
	v_mov_b64_e32 v[68:69], v[4:5]
	v_mov_b64_e32 v[100:101], v[4:5]
	v_mov_b32_e32 v202, 0xf149f2ca
	v_mov_b32_e32 v129, v128
	v_mov_b32_e32 v130, v128
	v_mov_b32_e32 v131, v128
	v_mov_b32_e32 v124, v128
	v_mov_b32_e32 v125, v128
	v_mov_b32_e32 v126, v128
	v_mov_b32_e32 v127, v128
	v_mov_b32_e32 v104, v128
	v_mov_b32_e32 v105, v128
	v_mov_b32_e32 v106, v128
	v_mov_b32_e32 v107, v128
	s_waitcnt vmcnt(3)
	ds_write_b128 v232, v[40:43]
	s_waitcnt vmcnt(1)
	ds_write_b128 v165, v[44:47] offset:17408
	ds_write_b128 v222, v[48:51]
	s_waitcnt vmcnt(0)
	ds_write_b128 v223, v[52:55] offset:17408
	v_mov_b64_e32 v[42:43], v[6:7]
	v_mov_b64_e32 v[46:47], v[6:7]
	v_mov_b64_e32 v[50:51], v[6:7]
	v_mov_b64_e32 v[54:55], v[6:7]
	v_mov_b64_e32 v[40:41], v[4:5]
	v_mov_b64_e32 v[44:45], v[4:5]
	v_mov_b64_e32 v[48:49], v[4:5]
	v_mov_b64_e32 v[52:53], v[4:5]
	s_cmp_eq_u64 s[6:7], 0
	s_cbranch_scc1 .Lmy_rotA_win
	s_ff1_i32_b64 s100, s[6:7]
	s_lshl_b32 s99, s100, 6
	s_lshl_b32 s100, s100, 7
	s_mov_b32 s101, 0
	v_or_b32_e32 v114, s99, v231
	v_or_b32_e32 v122, s99, v211
	v_lshlrev_b32_e32 v114, 8, v114
	v_lshlrev_b32_e32 v122, 8, v122
	v_mov_b32_e32 v115, 0
	v_mov_b32_e32 v123, 0
	v_lshl_add_u64 v[112:113], v[192:193], 0, v[114:115]
	v_lshl_add_u64 v[108:109], v[198:199], 0, s[100:101]
	v_lshl_add_u64 v[120:121], v[192:193], 0, v[122:123]
	v_lshl_add_u64 v[116:117], v[190:191], 0, s[100:101]
	s_waitcnt vmcnt(0)
	global_load_dwordx4 v[112:115], v[112:113], off
	global_load_dwordx4 v[108:111], v[108:109], off
	global_load_dwordx4 v[120:123], v[120:121], off
	global_load_dwordx4 v[116:119], v[116:117], off

; #define LAS __attribute__((address_space(3)))
; template <int MODE, class MaskF> ...
;     ...
;     const LAS unsigned char* kbase = buf + l15 * KS_STRIDE + lg * 16;
;     bf16x8 kf[2][2];
; #pragma unroll
;     for (int q = 0; q < 2; ++q) kf[0][q] = *(const LAS bf16x8*)(kbase + q * 16 * KS_STRIDE);
; #pragma unroll
;     for (int h = 0; h < 8; ++h) { const int ks = h >> 1, n0 = (h & 1) * 2;
;         if (h < 7) { const int ks1 = (h + 1) >> 1, n1 = ((h + 1) & 1) * 2;
; #pragma unroll
;             for (int q = 0; q < 2; ++q) kf[(h + 1) & 1][q] = *(const LAS bf16x8*)(kbase + (n1 + q) * 16 * KS_STRIDE + ks1 * 64); }
;         __builtin_amdgcn_sched_barrier(0);
;         __builtin_amdgcn_s_setprio(1);
; #pragma unroll
;         for (int q = 0; q < 2; ++q)
; #pragma unroll
;             for (int mi = 0; mi < 2; ++mi) S[n0 + q][mi] = __builtin_amdgcn_mfma_f32_16x16x32_bf16(kf[h & 1][q], Qf[mi][ks], S[n0 + q][mi], 0, 0, 0);
;         __builtin_amdgcn_s_setprio(0);
;         __builtin_amdgcn_sched_barrier(0);
;     }
;     const float NEG = -__builtin_inff();
;     float mx[2] = {NEG, NEG};
;     if (mf.need(kb)) {
; #pragma unroll
;         for (int nt = 0; nt < 4; ++nt)
; #pragma unroll
;             for (int mi = 0; mi < 2; ++mi)
; #pragma unroll
;                 for (int r = 0; r < 4; ++r) { const float sv = mf.valid(kb, 16 * nt + 4 * lg + r, mi) ? S[nt][mi][r] : NEG; S[nt][mi][r] = sv; mx[mi] = fmaxf(mx[mi], sv); }
;     } else {
; #pragma unroll
;         for (int nt = 0; nt < 4; ++nt)
; #pragma unroll
;             for (int mi = 0; mi < 2; ++mi)
; #pragma unroll
;                 for (int r = 0; r < 4; ++r) mx[mi] = fmaxf(mx[mi], S[nt][mi][r]);
.LBB0_2337:
.Lnopf_win:
	s_mul_i32 s0, s25, 0x8c00
	s_add_i32 s39, s0, 0
	v_add3_u32 v4, s39, v3, v230
	ds_read_b128 v[132:135], v4
	ds_read_b128 v[136:139], v4 offset:4352
	ds_read_b128 v[140:143], v4 offset:8704
	ds_read_b128 v[144:147], v4 offset:13056
	s_setprio 1
	s_waitcnt lgkmcnt(3)
	v_mfma_f32_16x16x32_bf16 v[148:151], v[132:135], v[8:11], 0
	v_mfma_f32_16x16x32_bf16 v[132:135], v[132:135], v[24:27], 0
	s_waitcnt lgkmcnt(2)
	v_mfma_f32_16x16x32_bf16 v[152:155], v[136:139], v[8:11], 0
	v_mfma_f32_16x16x32_bf16 v[136:139], v[136:139], v[24:27], 0
	s_setprio 0
	ds_read_b128 v[156:159], v4 offset:64
	ds_read_b128 v[160:163], v4 offset:4416
	s_setprio 1
	s_waitcnt lgkmcnt(3)
	v_mfma_f32_16x16x32_bf16 v[166:169], v[140:143], v[8:11], 0
	v_mfma_f32_16x16x32_bf16 v[140:143], v[140:143], v[24:27], 0
	s_waitcnt lgkmcnt(2)
	v_mfma_f32_16x16x32_bf16 v[218:221], v[144:147], v[8:11], 0
	v_mfma_f32_16x16x32_bf16 v[144:147], v[144:147], v[24:27], 0
	s_setprio 0
	ds_read_b128 v[234:237], v4 offset:8768
	ds_read_b128 v[238:241], v4 offset:13120
	s_setprio 1
	s_waitcnt lgkmcnt(3)
	v_mfma_f32_16x16x32_bf16 v[148:151], v[156:159], v[12:15], v[148:151]
	v_mfma_f32_16x16x32_bf16 v[132:135], v[156:159], v[28:31], v[132:135]
	s_waitcnt lgkmcnt(2)
	v_mfma_f32_16x16x32_bf16 v[152:155], v[160:163], v[12:15], v[152:155]
	v_mfma_f32_16x16x32_bf16 v[136:139], v[160:163], v[28:31], v[136:139]
	s_setprio 0
	ds_read_b128 v[156:159], v4 offset:128
	ds_read_b128 v[160:163], v4 offset:4480
	s_setprio 1
	s_waitcnt lgkmcnt(3)
	v_mfma_f32_16x16x32_bf16 v[140:143], v[234:237], v[28:31], v[140:143]
	s_waitcnt lgkmcnt(2)
	v_mfma_f32_16x16x32_bf16 v[144:147], v[238:241], v[28:31], v[144:147]
	v_mfma_f32_16x16x32_bf16 v[166:169], v[234:237], v[12:15], v[166:169]
	v_mfma_f32_16x16x32_bf16 v[218:221], v[238:241], v[12:15], v[218:221]
	s_setprio 0
	ds_read_b128 v[234:237], v4 offset:8832
	ds_read_b128 v[238:241], v4 offset:13184
	s_setprio 1
	s_waitcnt lgkmcnt(3)
	v_mfma_f32_16x16x32_bf16 v[148:151], v[156:159], v[16:19], v[148:151]
	v_mfma_f32_16x16x32_bf16 v[132:135], v[156:159], v[32:35], v[132:135]
	s_waitcnt lgkmcnt(2)
	v_mfma_f32_16x16x32_bf16 v[152:155], v[160:163], v[16:19], v[152:155]
	v_mfma_f32_16x16x32_bf16 v[136:139], v[160:163], v[32:35], v[136:139]
	s_setprio 0
	ds_read_b128 v[156:159], v4 offset:192
	ds_read_b128 v[160:163], v4 offset:4544
	s_setprio 1
	s_waitcnt lgkmcnt(3)
	v_mfma_f32_16x16x32_bf16 v[166:169], v[234:237], v[16:19], v[166:169]
	v_mfma_f32_16x16x32_bf16 v[234:237], v[234:237], v[32:35], v[140:143]
	s_waitcnt lgkmcnt(2)
	v_mfma_f32_16x16x32_bf16 v[218:221], v[238:241], v[16:19], v[218:221]
	v_mfma_f32_16x16x32_bf16 v[238:241], v[238:241], v[32:35], v[144:147]
	s_setprio 0
	ds_read_b128 v[242:245], v4 offset:8896
	ds_read_b128 v[246:249], v4 offset:13248
	s_setprio 1
	s_waitcnt lgkmcnt(3)
	v_mfma_f32_16x16x32_bf16 v[148:151], v[156:159], v[20:23], v[148:151]
	v_mfma_f32_16x16x32_bf16 v[144:147], v[156:159], v[36:39], v[132:135]
	s_waitcnt lgkmcnt(2)
	v_mfma_f32_16x16x32_bf16 v[152:155], v[160:163], v[20:23], v[152:155]
	v_mfma_f32_16x16x32_bf16 v[140:143], v[160:163], v[36:39], v[136:139]
	s_setprio 0
	s_setprio 1
	s_waitcnt lgkmcnt(1)
	v_mfma_f32_16x16x32_bf16 v[156:159], v[242:245], v[20:23], v[166:169]
	v_mfma_f32_16x16x32_bf16 v[136:139], v[242:245], v[36:39], v[234:237]
	s_waitcnt lgkmcnt(0)
	v_mfma_f32_16x16x32_bf16 v[160:163], v[246:249], v[20:23], v[218:221]
	v_mfma_f32_16x16x32_bf16 v[132:135], v[246:249], v[36:39], v[238:241]
	s_setprio 0
	s_cmp_eq_u32 s38, s37
	s_cselect_b64 s[0:1], -1, 0
	s_cmp_le_i32 s38, s24
	s_cselect_b64 s[10:11], -1, 0
	s_or_b64 s[10:11], s[0:1], s[10:11]
	s_mov_b64 s[0:1], -1
	s_and_b64 vcc, exec, s[10:11]
	s_cbranch_vccnz .LBB0_2339
	v_max3_f32 v4, v148, s29, v149
	v_max3_f32 v4, v4, v150, v151
	v_max3_f32 v6, v144, s29, v145
	v_max3_f32 v6, v6, v146, v147
	v_max3_f32 v4, v4, v152, v153
	v_max3_f32 v4, v4, v154, v155
	v_max3_f32 v6, v6, v140, v141
	v_max3_f32 v6, v6, v142, v143
	v_max3_f32 v4, v4, v156, v157
	v_max3_f32 v4, v4, v158, v159
	v_max3_f32 v6, v6, v136, v137
	v_max3_f32 v7, v6, v138, v139
	v_max3_f32 v4, v4, v160, v161
	v_max3_f32 v6, v4, v162, v163
	v_max3_f32 v4, v7, v132, v133
	v_max3_f32 v7, v4, v134, v135
	s_mov_b64 s[0:1], 0

; #define LAS __attribute__((address_space(3)))
; template <int MODE, class MaskF> ...
;     ...
;         const bool more = tiles != 0ull; int nkb = 0;
;         if (more) { nkb = __builtin_ctzll(tiles); tiles &= tiles - 1ull; }
;         bf16x8 Pf[2][2];
;         tile_qk<MODE>(lds + cur * BUF_BYTES, Qf, O, m, l, invl, kb, mf, (LAS float*)(lds + PS_OFF), wave, l15, lg, Pf, OL);
;         __builtin_amdgcn_sched_barrier(0);
;         Stage st;
;         if (more) load_tile<MODE != 1>(src, nkb * 64, tid, st);
;         if constexpr (MODE != 1) tile_pv(lds + cur * BUF_BYTES, Pf, O, l15, lg, OL, MODE == 0);
;         if (more) store_tile<MODE != 1>(lds + (cur ^ 1) * BUF_BYTES, tid, st);
;         __syncthreads();
;         if (!more) break;
;         kb = nkb; cur ^= 1;
;     }
.LBB0_2349:
	s_add_u32 s10, s6, -1
	s_addc_u32 s11, s7, -1
	s_and_b64 s[6:7], s[10:11], s[6:7]
	s_andn2_b64 vcc, exec, s[0:1]
	s_cmp_eq_u64 s[6:7], 0
	s_cbranch_scc1 .Lmy_rotB_win
	s_ff1_i32_b64 s100, s[6:7]
	s_lshl_b32 s99, s100, 6
	s_lshl_b32 s100, s100, 7
	s_mov_b32 s101, 0
	v_or_b32_e32 v114, s99, v231
	v_or_b32_e32 v122, s99, v211
	v_lshlrev_b32_e32 v114, 8, v114
	v_lshlrev_b32_e32 v122, 8, v122
	v_mov_b32_e32 v115, 0
	v_mov_b32_e32 v123, 0
	v_lshl_add_u64 v[112:113], v[192:193], 0, v[114:115]
	v_lshl_add_u64 v[108:109], v[198:199], 0, s[100:101]
	v_lshl_add_u64 v[120:121], v[192:193], 0, v[122:123]
	v_lshl_add_u64 v[116:117], v[190:191], 0, s[100:101]
	s_waitcnt vmcnt(0)
	global_load_dwordx4 v[112:115], v[112:113], off
	global_load_dwordx4 v[108:111], v[108:109], off
	global_load_dwordx4 v[120:123], v[120:121], off
	global_load_dwordx4 v[116:119], v[116:117], off
.Lmy_rotB_win:
	v_mov_b32_e32 v124, v128
	v_mov_b32_e32 v125, v129
	v_mov_b32_e32 v126, v130
	v_mov_b32_e32 v127, v131
	s_waitcnt lgkmcnt(0)
	s_barrier
	s_cbranch_vccz .LBB0_2307
	s_branch .LBB0_2337
